# plus: first K iteration of each big-GEMM unit peeled with srcC=0, 127 accumulator-zeroing v_mov per unit removed
# speedup vs baseline: 1.0123x; 1.0026x over previous
.LBB0_270:
	s_ashr_i32 s11, s10, 31
	v_cmp_lt_i64_e32 vcc, s[14:15], v[152:153]
	s_lshl_b64 s[14:15], s[10:11], 19
	s_add_u32 s14, s68, s14
	s_addc_u32 s15, s69, s15
	s_and_b64 s[20:21], vcc, exec
	s_cselect_b32 s11, s15, s5
	s_cselect_b32 s43, s14, s4
	s_ashr_i32 s3, s2, 31
	s_lshl_b64 s[20:21], s[2:3], 19
	s_add_u32 s22, s25, s20
	s_addc_u32 s23, s36, s21
	s_and_b64 s[20:21], vcc, exec
	s_cselect_b32 s3, s23, s9
	s_cselect_b32 s73, s22, s8
	s_add_u32 s4, s4, 0x40080
	s_addc_u32 s5, s5, 0
	s_add_u32 s74, s8, 0x100
	v_mov_b32_e32 v0, 0
	s_addc_u32 s75, s9, 0
	s_mov_b32 s78, -2
	s_waitcnt lgkmcnt(0)
	s_add_u32 s8, s4, 0xfffc0080
	s_addc_u32 s9, s5, -1
	s_add_i32 s79, 0, 0x10000
	v_add_u32_e32 v142, s79, v159
	ds_read_b128 v[138:141], v142
	ds_read_b128 v[162:165], v142 offset:1024
	ds_read_b128 v[166:169], v142 offset:2048
	ds_read_b128 v[170:173], v142 offset:3072
	s_cmp_eq_u32 s78, 12
	s_cselect_b32 s21, s11, s9
	s_cselect_b32 s20, s43, s8
	s_cselect_b32 s9, s3, s75
	s_cselect_b32 s8, s73, s74
	v_lshl_add_u64 v[142:143], s[4:5], 0, v[134:135]
	s_add_i32 m0, s44, 0xc000
	ds_read_b128 v[188:191], v161
	ds_read_b128 v[192:195], v161 offset:1024
	ds_read_b128 v[196:199], v161 offset:2048
	ds_read_b128 v[200:203], v161 offset:3072
	ds_read_b128 v[204:207], v161 offset:4096
	ds_read_b128 v[208:211], v161 offset:5120
	ds_read_b128 v[212:215], v161 offset:6144
	ds_read_b128 v[216:219], v161 offset:7168
	global_load_lds_dwordx4 v[142:143], off
	v_lshl_add_u64 v[142:143], s[4:5], 0, v[136:137]
	s_add_i32 m0, s44, 0xe000
	s_nop 0
	global_load_lds_dwordx4 v[142:143], off
	s_waitcnt lgkmcnt(8)
	s_barrier
	s_waitcnt lgkmcnt(0)
	s_setprio 1
	s_waitcnt lgkmcnt(0)
	v_mfma_f32_16x16x32_bf16 v[124:127], v[138:141], v[188:191], 0
	v_mfma_f32_16x16x32_bf16 v[120:123], v[166:169], v[188:191], 0
	v_mfma_f32_16x16x32_bf16 v[108:111], v[138:141], v[196:199], 0
	v_mfma_f32_16x16x32_bf16 v[104:107], v[166:169], v[196:199], 0
	v_mfma_f32_16x16x32_bf16 v[92:95], v[138:141], v[204:207], 0
	v_mfma_f32_16x16x32_bf16 v[88:91], v[166:169], v[204:207], 0
	v_mfma_f32_16x16x32_bf16 v[76:79], v[138:141], v[212:215], 0
	v_mfma_f32_16x16x32_bf16 v[72:75], v[166:169], v[212:215], 0
	v_mfma_f32_16x16x32_bf16 v[124:127], v[162:165], v[192:195], v[124:127]
	v_mfma_f32_16x16x32_bf16 v[120:123], v[170:173], v[192:195], v[120:123]
	v_mfma_f32_16x16x32_bf16 v[108:111], v[162:165], v[200:203], v[108:111]
	v_mfma_f32_16x16x32_bf16 v[104:107], v[170:173], v[200:203], v[104:107]
	v_mfma_f32_16x16x32_bf16 v[92:95], v[162:165], v[208:211], v[92:95]
	v_mfma_f32_16x16x32_bf16 v[88:91], v[170:173], v[208:211], v[88:91]
	v_mfma_f32_16x16x32_bf16 v[76:79], v[162:165], v[216:219], v[76:79]
	v_mfma_f32_16x16x32_bf16 v[72:75], v[170:173], v[216:219], v[72:75]
	s_setprio 0
	s_barrier
	s_add_i32 s84, 0, 0x14000
	v_add_u32_e32 v142, s84, v159
	s_add_i32 s79, s79, s37
	ds_read_b128 v[220:223], v142
	ds_read_b128 v[224:227], v142 offset:1024
	ds_read_b128 v[228:231], v142 offset:2048
	ds_read_b128 v[232:235], v142 offset:3072
	v_lshl_add_u64 v[142:143], s[8:9], 0, v[148:149]
	s_mov_b32 m0, s79
	v_lshl_add_u64 v[174:175], s[8:9], 0, v[128:129]
	global_load_lds_dwordx4 v[142:143], off
	s_add_i32 m0, s79, 0x2000
	s_nop 0
	global_load_lds_dwordx4 v[174:175], off
	s_barrier
	s_waitcnt lgkmcnt(0)
	s_setprio 1
	s_waitcnt lgkmcnt(0)
	v_mfma_f32_16x16x32_bf16 v[116:119], v[220:223], v[188:191], 0
	v_mfma_f32_16x16x32_bf16 v[112:115], v[228:231], v[188:191], 0
	v_mfma_f32_16x16x32_bf16 v[100:103], v[220:223], v[196:199], 0
	v_mfma_f32_16x16x32_bf16 v[96:99], v[228:231], v[196:199], 0
	v_mfma_f32_16x16x32_bf16 v[84:87], v[220:223], v[204:207], 0
	v_mfma_f32_16x16x32_bf16 v[80:83], v[228:231], v[204:207], 0
	v_mfma_f32_16x16x32_bf16 v[68:71], v[220:223], v[212:215], 0
	v_mfma_f32_16x16x32_bf16 v[64:67], v[228:231], v[212:215], 0
	v_mfma_f32_16x16x32_bf16 v[116:119], v[224:227], v[192:195], v[116:119]
	v_mfma_f32_16x16x32_bf16 v[112:115], v[232:235], v[192:195], v[112:115]
	v_mfma_f32_16x16x32_bf16 v[100:103], v[224:227], v[200:203], v[100:103]
	v_mfma_f32_16x16x32_bf16 v[96:99], v[232:235], v[200:203], v[96:99]
	v_mfma_f32_16x16x32_bf16 v[84:87], v[224:227], v[208:211], v[84:87]
	v_mfma_f32_16x16x32_bf16 v[80:83], v[232:235], v[208:211], v[80:83]
	v_mfma_f32_16x16x32_bf16 v[68:71], v[224:227], v[216:219], v[68:71]
	v_mfma_f32_16x16x32_bf16 v[64:67], v[232:235], v[216:219], v[64:67]
	s_setprio 0
	s_mov_b32 m0, s44
	v_lshl_add_u64 v[236:237], s[20:21], 0, v[132:133]
	s_barrier
	ds_read_b128 v[188:191], v161 offset:16384
	ds_read_b128 v[192:195], v161 offset:17408
	ds_read_b128 v[196:199], v161 offset:18432
	ds_read_b128 v[200:203], v161 offset:19456
	ds_read_b128 v[204:207], v161 offset:20480
	ds_read_b128 v[208:211], v161 offset:21504
	ds_read_b128 v[212:215], v161 offset:22528
	ds_read_b128 v[216:219], v161 offset:23552
	global_load_lds_dwordx4 v[236:237], off
	v_lshl_add_u64 v[238:239], s[20:21], 0, v[130:131]
	s_mov_b32 m0, s45
	s_nop 0
	global_load_lds_dwordx4 v[238:239], off
	s_barrier
	s_waitcnt lgkmcnt(0)
	s_setprio 1
	s_waitcnt lgkmcnt(0)
	v_mfma_f32_16x16x32_bf16 v[60:63], v[138:141], v[188:191], 0
	v_mfma_f32_16x16x32_bf16 v[56:59], v[166:169], v[188:191], 0
	v_mfma_f32_16x16x32_bf16 v[44:47], v[138:141], v[196:199], 0
	v_mfma_f32_16x16x32_bf16 v[40:43], v[166:169], v[196:199], 0
	v_mfma_f32_16x16x32_bf16 v[28:31], v[138:141], v[204:207], 0
	v_mfma_f32_16x16x32_bf16 v[24:27], v[166:169], v[204:207], 0
	v_mfma_f32_16x16x32_bf16 v[12:15], v[138:141], v[212:215], 0
	v_mfma_f32_16x16x32_bf16 v[8:11], v[166:169], v[212:215], 0
	v_mfma_f32_16x16x32_bf16 v[60:63], v[162:165], v[192:195], v[60:63]
	v_mfma_f32_16x16x32_bf16 v[56:59], v[170:173], v[192:195], v[56:59]
	v_mfma_f32_16x16x32_bf16 v[44:47], v[162:165], v[200:203], v[44:47]
	v_mfma_f32_16x16x32_bf16 v[40:43], v[170:173], v[200:203], v[40:43]
	v_mfma_f32_16x16x32_bf16 v[28:31], v[162:165], v[208:211], v[28:31]
	v_mfma_f32_16x16x32_bf16 v[24:27], v[170:173], v[208:211], v[24:27]
	v_mfma_f32_16x16x32_bf16 v[12:15], v[162:165], v[216:219], v[12:15]
	v_mfma_f32_16x16x32_bf16 v[8:11], v[170:173], v[216:219], v[8:11]
	s_setprio 0
	s_barrier
	s_add_u32 s80, s8, 0x40000
	s_addc_u32 s81, s9, 0
	s_add_i32 s79, s84, s37
	v_lshl_add_u64 v[138:139], s[80:81], 0, v[148:149]
	s_mov_b32 m0, s79
	s_nop 0
	global_load_lds_dwordx4 v[138:139], off
	v_lshl_add_u64 v[138:139], s[80:81], 0, v[128:129]
	s_add_i32 m0, s79, 0x2000
	s_nop 0
	global_load_lds_dwordx4 v[138:139], off
	s_waitcnt vmcnt(6)
	s_barrier
	s_setprio 1
	v_mfma_f32_16x16x32_bf16 v[52:55], v[220:223], v[188:191], 0
	v_mfma_f32_16x16x32_bf16 v[48:51], v[228:231], v[188:191], 0
	v_mfma_f32_16x16x32_bf16 v[36:39], v[220:223], v[196:199], 0
	v_mfma_f32_16x16x32_bf16 v[32:35], v[228:231], v[196:199], 0
	v_mfma_f32_16x16x32_bf16 v[20:23], v[220:223], v[204:207], 0
	v_mfma_f32_16x16x32_bf16 v[16:19], v[228:231], v[204:207], 0
	v_mfma_f32_16x16x32_bf16 v[4:7], v[220:223], v[212:215], 0
	v_mfma_f32_16x16x32_bf16 v[0:3], v[228:231], v[212:215], 0
	v_mfma_f32_16x16x32_bf16 v[52:55], v[224:227], v[192:195], v[52:55]
	v_mfma_f32_16x16x32_bf16 v[48:51], v[232:235], v[192:195], v[48:51]
	v_mfma_f32_16x16x32_bf16 v[36:39], v[224:227], v[200:203], v[36:39]
	v_mfma_f32_16x16x32_bf16 v[32:35], v[232:235], v[200:203], v[32:35]
	v_mfma_f32_16x16x32_bf16 v[20:23], v[224:227], v[208:211], v[20:23]
	v_mfma_f32_16x16x32_bf16 v[16:19], v[232:235], v[208:211], v[16:19]
	v_mfma_f32_16x16x32_bf16 v[4:7], v[224:227], v[216:219], v[4:7]
	v_mfma_f32_16x16x32_bf16 v[0:3], v[232:235], v[216:219], v[0:3]
	s_setprio 0
	s_add_i32 s79, 0, 0x18000
	v_add_u32_e32 v170, s79, v159
	s_barrier
	ds_read_b128 v[138:141], v170
	ds_read_b128 v[162:165], v170 offset:1024
	ds_read_b128 v[166:169], v170 offset:2048
	ds_read_b128 v[170:173], v170 offset:3072
	s_add_u32 s20, s20, 0x40000
	s_addc_u32 s21, s21, 0
	s_mov_b32 m0, s46
	v_lshl_add_u64 v[220:221], s[20:21], 0, v[132:133]
	ds_read_b128 v[188:191], v161 offset:32768
	ds_read_b128 v[192:195], v161 offset:33792
	ds_read_b128 v[196:199], v161 offset:34816
	ds_read_b128 v[200:203], v161 offset:35840
	ds_read_b128 v[204:207], v161 offset:36864
	ds_read_b128 v[208:211], v161 offset:37888
	ds_read_b128 v[212:215], v161 offset:38912
	ds_read_b128 v[216:219], v161 offset:39936
	global_load_lds_dwordx4 v[220:221], off
	v_lshl_add_u64 v[220:221], s[20:21], 0, v[130:131]
	s_mov_b32 m0, s47
	s_nop 0
	global_load_lds_dwordx4 v[220:221], off
	s_waitcnt lgkmcnt(8)
	s_barrier
	s_waitcnt lgkmcnt(0)
	s_setprio 1
	s_waitcnt lgkmcnt(0)
	v_mfma_f32_16x16x32_bf16 v[124:127], v[138:141], v[188:191], v[124:127]
	v_mfma_f32_16x16x32_bf16 v[120:123], v[166:169], v[188:191], v[120:123]
	v_mfma_f32_16x16x32_bf16 v[108:111], v[138:141], v[196:199], v[108:111]
	v_mfma_f32_16x16x32_bf16 v[104:107], v[166:169], v[196:199], v[104:107]
	v_mfma_f32_16x16x32_bf16 v[92:95], v[138:141], v[204:207], v[92:95]
	v_mfma_f32_16x16x32_bf16 v[88:91], v[166:169], v[204:207], v[88:91]
	v_mfma_f32_16x16x32_bf16 v[76:79], v[138:141], v[212:215], v[76:79]
	v_mfma_f32_16x16x32_bf16 v[72:75], v[166:169], v[212:215], v[72:75]
	v_mfma_f32_16x16x32_bf16 v[124:127], v[162:165], v[192:195], v[124:127]
	v_mfma_f32_16x16x32_bf16 v[120:123], v[170:173], v[192:195], v[120:123]
	v_mfma_f32_16x16x32_bf16 v[108:111], v[162:165], v[200:203], v[108:111]
	v_mfma_f32_16x16x32_bf16 v[104:107], v[170:173], v[200:203], v[104:107]
	v_mfma_f32_16x16x32_bf16 v[92:95], v[162:165], v[208:211], v[92:95]
	v_mfma_f32_16x16x32_bf16 v[88:91], v[170:173], v[208:211], v[88:91]
	v_mfma_f32_16x16x32_bf16 v[76:79], v[162:165], v[216:219], v[76:79]
	v_mfma_f32_16x16x32_bf16 v[72:75], v[170:173], v[216:219], v[72:75]
	s_setprio 0
	s_barrier
	s_add_i32 s20, 0, 0x1c000
	s_add_i32 s21, s79, s37
	v_add_u32_e32 v232, s20, v159
	v_lshl_add_u64 v[142:143], v[142:143], 0, s[28:29]
	s_mov_b32 m0, s21
	ds_read_b128 v[220:223], v232
	ds_read_b128 v[224:227], v232 offset:1024
	ds_read_b128 v[228:231], v232 offset:2048
	ds_read_b128 v[232:235], v232 offset:3072
	global_load_lds_dwordx4 v[142:143], off
	v_lshl_add_u64 v[142:143], v[174:175], 0, s[28:29]
	s_add_i32 m0, s21, 0x2000
	s_nop 0
	global_load_lds_dwordx4 v[142:143], off
	s_barrier
	s_waitcnt lgkmcnt(0)
	s_setprio 1
	s_waitcnt lgkmcnt(0)
	v_mfma_f32_16x16x32_bf16 v[116:119], v[220:223], v[188:191], v[116:119]
	v_mfma_f32_16x16x32_bf16 v[112:115], v[228:231], v[188:191], v[112:115]
	v_mfma_f32_16x16x32_bf16 v[100:103], v[220:223], v[196:199], v[100:103]
	v_mfma_f32_16x16x32_bf16 v[96:99], v[228:231], v[196:199], v[96:99]
	v_mfma_f32_16x16x32_bf16 v[84:87], v[220:223], v[204:207], v[84:87]
	v_mfma_f32_16x16x32_bf16 v[80:83], v[228:231], v[204:207], v[80:83]
	v_mfma_f32_16x16x32_bf16 v[68:71], v[220:223], v[212:215], v[68:71]
	v_mfma_f32_16x16x32_bf16 v[64:67], v[228:231], v[212:215], v[64:67]
	v_mfma_f32_16x16x32_bf16 v[116:119], v[224:227], v[192:195], v[116:119]
	v_mfma_f32_16x16x32_bf16 v[112:115], v[232:235], v[192:195], v[112:115]
	v_mfma_f32_16x16x32_bf16 v[100:103], v[224:227], v[200:203], v[100:103]
	v_mfma_f32_16x16x32_bf16 v[96:99], v[232:235], v[200:203], v[96:99]
	v_mfma_f32_16x16x32_bf16 v[84:87], v[224:227], v[208:211], v[84:87]
	v_mfma_f32_16x16x32_bf16 v[80:83], v[232:235], v[208:211], v[80:83]
	v_mfma_f32_16x16x32_bf16 v[68:71], v[224:227], v[216:219], v[68:71]
	v_mfma_f32_16x16x32_bf16 v[64:67], v[232:235], v[216:219], v[64:67]
	s_setprio 0
	s_mov_b32 m0, s51
	v_lshl_add_u64 v[142:143], v[236:237], 0, s[28:29]
	s_barrier
	ds_read_b128 v[188:191], v161 offset:49152
	ds_read_b128 v[192:195], v161 offset:50176
	ds_read_b128 v[196:199], v161 offset:51200
	ds_read_b128 v[200:203], v161 offset:52224
	ds_read_b128 v[204:207], v161 offset:53248
	ds_read_b128 v[208:211], v161 offset:54272
	ds_read_b128 v[212:215], v161 offset:55296
	ds_read_b128 v[216:219], v161 offset:56320
	global_load_lds_dwordx4 v[142:143], off
	v_lshl_add_u64 v[142:143], v[238:239], 0, s[28:29]
	s_mov_b32 m0, s64
	s_nop 0
	global_load_lds_dwordx4 v[142:143], off
	s_barrier
	s_waitcnt lgkmcnt(0)
	s_setprio 1
	s_waitcnt lgkmcnt(0)
	v_mfma_f32_16x16x32_bf16 v[60:63], v[138:141], v[188:191], v[60:63]
	v_mfma_f32_16x16x32_bf16 v[56:59], v[166:169], v[188:191], v[56:59]
	v_mfma_f32_16x16x32_bf16 v[44:47], v[138:141], v[196:199], v[44:47]
	v_mfma_f32_16x16x32_bf16 v[40:43], v[166:169], v[196:199], v[40:43]
	v_mfma_f32_16x16x32_bf16 v[28:31], v[138:141], v[204:207], v[28:31]
	v_mfma_f32_16x16x32_bf16 v[24:27], v[166:169], v[204:207], v[24:27]
	v_mfma_f32_16x16x32_bf16 v[12:15], v[138:141], v[212:215], v[12:15]
	v_mfma_f32_16x16x32_bf16 v[8:11], v[166:169], v[212:215], v[8:11]
	v_mfma_f32_16x16x32_bf16 v[60:63], v[162:165], v[192:195], v[60:63]
	v_mfma_f32_16x16x32_bf16 v[56:59], v[170:173], v[192:195], v[56:59]
	v_mfma_f32_16x16x32_bf16 v[44:47], v[162:165], v[200:203], v[44:47]
	v_mfma_f32_16x16x32_bf16 v[40:43], v[170:173], v[200:203], v[40:43]
	v_mfma_f32_16x16x32_bf16 v[28:31], v[162:165], v[208:211], v[28:31]
	v_mfma_f32_16x16x32_bf16 v[24:27], v[170:173], v[208:211], v[24:27]
	v_mfma_f32_16x16x32_bf16 v[12:15], v[162:165], v[216:219], v[12:15]
	v_mfma_f32_16x16x32_bf16 v[8:11], v[170:173], v[216:219], v[8:11]
	s_setprio 0
	s_barrier
	s_add_u32 s8, s8, 0x40080
	s_addc_u32 s9, s9, 0
	s_add_i32 s20, s20, s37
	v_lshl_add_u64 v[138:139], s[8:9], 0, v[148:149]
	s_mov_b32 m0, s20
	s_nop 0
	global_load_lds_dwordx4 v[138:139], off
	v_lshl_add_u64 v[138:139], s[8:9], 0, v[128:129]
	s_add_i32 m0, s20, 0x2000
	s_nop 0
	global_load_lds_dwordx4 v[138:139], off
	s_waitcnt vmcnt(6)
	s_barrier
	s_setprio 1
	v_mfma_f32_16x16x32_bf16 v[52:55], v[220:223], v[188:191], v[52:55]
	v_mfma_f32_16x16x32_bf16 v[48:51], v[228:231], v[188:191], v[48:51]
	v_mfma_f32_16x16x32_bf16 v[36:39], v[220:223], v[196:199], v[36:39]
	v_mfma_f32_16x16x32_bf16 v[32:35], v[228:231], v[196:199], v[32:35]
	v_mfma_f32_16x16x32_bf16 v[20:23], v[220:223], v[204:207], v[20:23]
	v_mfma_f32_16x16x32_bf16 v[16:19], v[228:231], v[204:207], v[16:19]
	v_mfma_f32_16x16x32_bf16 v[4:7], v[220:223], v[212:215], v[4:7]
	v_mfma_f32_16x16x32_bf16 v[0:3], v[228:231], v[212:215], v[0:3]
	v_mfma_f32_16x16x32_bf16 v[52:55], v[224:227], v[192:195], v[52:55]
	v_mfma_f32_16x16x32_bf16 v[48:51], v[232:235], v[192:195], v[48:51]
	v_mfma_f32_16x16x32_bf16 v[36:39], v[224:227], v[200:203], v[36:39]
	v_mfma_f32_16x16x32_bf16 v[32:35], v[232:235], v[200:203], v[32:35]
	v_mfma_f32_16x16x32_bf16 v[20:23], v[224:227], v[208:211], v[20:23]
	v_mfma_f32_16x16x32_bf16 v[16:19], v[232:235], v[208:211], v[16:19]
	v_mfma_f32_16x16x32_bf16 v[4:7], v[224:227], v[216:219], v[4:7]
	v_mfma_f32_16x16x32_bf16 v[0:3], v[232:235], v[216:219], v[0:3]
	s_setprio 0
	s_add_i32 s78, s78, 2
	s_add_u32 s4, s4, 0x100
	s_addc_u32 s5, s5, 0
	s_add_u32 s74, s74, 0x100
	s_addc_u32 s75, s75, 0
	s_cmp_gt_u32 s78, 13
	s_barrier
	s_cbranch_scc1 .Lpeel_after_g0

.Lpeel_after_g0:
	s_mov_b32 s4, 0xc0135761
	v_pk_mul_f32 v[162:163], v[126:127], v[126:127]
	v_pk_mul_f32 v[164:165], v[124:125], v[124:125]
	v_mov_b64_e32 v[166:167], s[4:5]
	s_mov_b32 s4, 0x3dd2d3e7
	v_pk_fma_f32 v[164:165], v[164:165], s[4:5], v[166:167] op_sel_hi:[1,0,0] neg_lo:[1,0,0] neg_hi:[1,0,0]
	v_pk_fma_f32 v[162:163], v[162:163], s[4:5], v[166:167] op_sel_hi:[1,0,0] neg_lo:[1,0,0] neg_hi:[1,0,0]
	v_pk_mul_f32 v[164:165], v[124:125], v[164:165]
	v_pk_mul_f32 v[162:163], v[126:127], v[162:163]
	v_exp_f32_e32 v164, v164
	v_exp_f32_e32 v165, v165
	v_exp_f32_e32 v162, v162
	v_exp_f32_e32 v163, v163
	v_lshl_add_u32 v140, s42, 8, v158
	v_pk_add_f32 v[164:165], v[164:165], 1.0 op_sel_hi:[1,0]
	v_ashrrev_i32_e32 v141, 31, v140
	v_pk_add_f32 v[162:163], v[162:163], 1.0 op_sel_hi:[1,0]
	v_rcp_f32_e32 v164, v164
	v_rcp_f32_e32 v165, v165
	v_rcp_f32_e32 v162, v162
	v_rcp_f32_e32 v163, v163
	v_lshl_or_b32 v138, s72, 8, v160
	v_pk_mul_f32 v[124:125], v[124:125], v[164:165]
	v_pk_mul_f32 v[164:165], v[120:121], v[120:121]
	v_pk_mul_f32 v[126:127], v[126:127], v[162:163]
	v_pk_mul_f32 v[162:163], v[122:123], v[122:123]
	v_pk_fma_f32 v[164:165], v[164:165], s[4:5], v[166:167] op_sel_hi:[1,0,0] neg_lo:[1,0,0] neg_hi:[1,0,0]
	v_pk_fma_f32 v[162:163], v[162:163], s[4:5], v[166:167] op_sel_hi:[1,0,0] neg_lo:[1,0,0] neg_hi:[1,0,0]
	v_pk_mul_f32 v[164:165], v[120:121], v[164:165]
	v_pk_mul_f32 v[162:163], v[122:123], v[162:163]
	v_exp_f32_e32 v164, v164
	v_exp_f32_e32 v165, v165
	v_exp_f32_e32 v162, v162
	v_exp_f32_e32 v163, v163
	v_lshlrev_b64 v[142:143], 13, v[140:141]
	v_pk_add_f32 v[164:165], v[164:165], 1.0 op_sel_hi:[1,0]
	v_ashrrev_i32_e32 v139, 31, v138
	v_pk_add_f32 v[162:163], v[162:163], 1.0 op_sel_hi:[1,0]
	v_rcp_f32_e32 v164, v164
	v_rcp_f32_e32 v165, v165
	v_rcp_f32_e32 v162, v162
	v_rcp_f32_e32 v163, v163
	v_lshl_add_u64 v[142:143], s[70:71], 0, v[142:143]
	v_lshl_add_u64 v[142:143], v[138:139], 1, v[142:143]
	v_pk_mul_f32 v[120:121], v[120:121], v[164:165]
	v_pk_mul_f32 v[122:123], v[122:123], v[162:163]
	v_cvt_pk_bf16_f32 v162, v124, v125
	v_cvt_pk_bf16_f32 v163, v126, v127
	v_cvt_pk_bf16_f32 v164, v120, v121
	s_cmp_gt_i32 s72, 7
	v_cvt_pk_bf16_f32 v165, v122, v123
	global_store_dwordx4 v[142:143], v[162:165], off
	s_nop 1
	v_pk_mul_f32 v[162:163], v[118:119], v[118:119]
	v_pk_mul_f32 v[164:165], v[116:117], v[116:117]
	v_pk_fma_f32 v[162:163], v[162:163], s[4:5], v[166:167] op_sel_hi:[1,0,0] neg_lo:[1,0,0] neg_hi:[1,0,0]
	v_pk_fma_f32 v[164:165], v[164:165], s[4:5], v[166:167] op_sel_hi:[1,0,0] neg_lo:[1,0,0] neg_hi:[1,0,0]
	v_pk_mul_f32 v[162:163], v[118:119], v[162:163]
	v_pk_mul_f32 v[164:165], v[116:117], v[164:165]
	v_exp_f32_e32 v162, v162
	v_exp_f32_e32 v164, v164
	v_exp_f32_e32 v165, v165
	v_exp_f32_e32 v163, v163
	v_pk_add_f32 v[164:165], v[164:165], 1.0 op_sel_hi:[1,0]
	v_pk_add_f32 v[162:163], v[162:163], 1.0 op_sel_hi:[1,0]
	v_rcp_f32_e32 v164, v164
	v_rcp_f32_e32 v165, v165
	v_rcp_f32_e32 v162, v162
	v_rcp_f32_e32 v163, v163
	v_pk_mul_f32 v[116:117], v[116:117], v[164:165]
	v_pk_mul_f32 v[164:165], v[112:113], v[112:113]
	v_pk_mul_f32 v[118:119], v[118:119], v[162:163]
	v_pk_mul_f32 v[162:163], v[114:115], v[114:115]
	v_pk_fma_f32 v[164:165], v[164:165], s[4:5], v[166:167] op_sel_hi:[1,0,0] neg_lo:[1,0,0] neg_hi:[1,0,0]
	v_pk_fma_f32 v[162:163], v[162:163], s[4:5], v[166:167] op_sel_hi:[1,0,0] neg_lo:[1,0,0] neg_hi:[1,0,0]
	v_pk_mul_f32 v[164:165], v[112:113], v[164:165]
	v_pk_mul_f32 v[162:163], v[114:115], v[162:163]
	v_exp_f32_e32 v164, v164
	v_exp_f32_e32 v165, v165
	v_exp_f32_e32 v162, v162
	v_exp_f32_e32 v163, v163
	s_cselect_b64 s[4:5], -1, 0
	v_pk_add_f32 v[164:165], v[164:165], 1.0 op_sel_hi:[1,0]
	s_cmp_lt_i32 s72, 8
	v_pk_add_f32 v[162:163], v[162:163], 1.0 op_sel_hi:[1,0]
	v_rcp_f32_e32 v164, v164
	v_rcp_f32_e32 v165, v165
	v_rcp_f32_e32 v162, v162
	v_rcp_f32_e32 v163, v163
	v_pk_mul_f32 v[112:113], v[112:113], v[164:165]
	s_nop 0
	v_cvt_pk_bf16_f32 v164, v112, v113
	v_pk_mul_f32 v[114:115], v[114:115], v[162:163]
	v_cvt_pk_bf16_f32 v162, v116, v117
	v_cvt_pk_bf16_f32 v163, v118, v119
	s_nop 0
	v_cvt_pk_bf16_f32 v165, v114, v115
	global_store_dwordx4 v[142:143], v[162:165], off offset:256
	s_cbranch_scc1 .LBB0_276
	v_pk_mul_f32 v[126:127], v[126:127], v[126:127]
	v_pk_mul_f32 v[118:119], v[118:119], v[118:119]
	v_pk_fma_f32 v[124:125], v[124:125], v[124:125], v[126:127]
	v_pk_fma_f32 v[116:117], v[116:117], v[116:117], v[118:119]
	v_pk_fma_f32 v[120:121], v[120:121], v[120:121], v[124:125]
	v_pk_fma_f32 v[112:113], v[112:113], v[112:113], v[116:117]
	v_pk_fma_f32 v[120:121], v[122:123], v[122:123], v[120:121]
	v_pk_fma_f32 v[112:113], v[114:115], v[114:115], v[112:113]
	v_and_b32_e32 v114, 64, v181
	v_add_f32_e32 v112, v112, v113
	v_add_f32_e32 v113, v120, v121
	v_add_f32_e32 v112, v113, v112
	v_xor_b32_e32 v113, 16, v181
	v_add_u32_e32 v114, 64, v114
	v_cmp_lt_i32_e32 vcc, v113, v114
	s_nop 1
	v_cndmask_b32_e32 v113, v181, v113, vcc
	v_lshlrev_b32_e32 v113, 2, v113
	ds_bpermute_b32 v113, v113, v112
	s_waitcnt lgkmcnt(0)
	v_add_f32_e32 v112, v112, v113
	v_xor_b32_e32 v113, 32, v181
	v_cmp_lt_i32_e32 vcc, v113, v114
	s_nop 1
	v_cndmask_b32_e32 v113, v181, v113, vcc
	v_lshlrev_b32_e32 v113, 2, v113
	ds_bpermute_b32 v113, v113, v112
	s_and_saveexec_b64 s[8:9], s[38:39]
	s_cbranch_execz .LBB0_275
	v_readlane_b32 s20, v246, 28
	s_waitcnt lgkmcnt(0)
	v_add_f32_e32 v114, v112, v113
	v_lshlrev_b64 v[112:113], 7, v[140:141]
	v_readlane_b32 s21, v246, 29
	s_lshl_b32 s84, s72, 2
	s_nop 0
	v_lshl_add_u64 v[112:113], s[20:21], 0, v[112:113]
	v_lshl_add_u64 v[112:113], s[84:85], 2, v[112:113]
	s_lshl_b32 s84, s50, 2
	v_lshl_add_u64 v[112:113], v[112:113], 0, s[84:85]
	global_store_dword v[112:113], v114, off offset:-128

.LBB0_489:
	s_add_u32 s0, s44, 0x80
	s_addc_u32 s1, s45, 0
	s_add_u32 vcc_lo, s42, 0x100
	v_mov_b32_e32 v0, 0
	s_addc_u32 vcc_hi, s43, 0
	s_mov_b32 s42, 0
	s_add_i32 s94, s42, 2
	s_add_u32 s44, s0, 0x80
	s_addc_u32 s43, s1, 0
	s_add_i32 s95, 0, 0x10000
	v_add_u32_e32 v140, s95, v173
	ds_read_b128 v[128:131], v140
	ds_read_b128 v[132:135], v140 offset:1024
	ds_read_b128 v[136:139], v140 offset:2048
	ds_read_b128 v[140:143], v140 offset:3072
	s_cmp_eq_u32 s79, s42
	s_cselect_b32 s42, s20, s44
	s_cselect_b32 s43, s21, s43
	s_cselect_b32 s45, s41, vcc_hi
	s_cselect_b32 s44, s40, vcc_lo
	v_lshl_add_u64 v[216:217], s[0:1], 0, v[164:165]
	s_add_i32 m0, s51, 0xc000
	ds_read_b128 v[168:171], v175
	ds_read_b128 v[188:191], v175 offset:1024
	ds_read_b128 v[192:195], v175 offset:2048
	ds_read_b128 v[196:199], v175 offset:3072
	ds_read_b128 v[200:203], v175 offset:4096
	ds_read_b128 v[204:207], v175 offset:5120
	ds_read_b128 v[208:211], v175 offset:6144
	ds_read_b128 v[212:215], v175 offset:7168
	global_load_lds_dwordx4 v[216:217], off
	v_lshl_add_u64 v[216:217], s[0:1], 0, v[166:167]
	s_add_i32 m0, s51, 0xe000
	s_nop 0
	global_load_lds_dwordx4 v[216:217], off
	s_waitcnt lgkmcnt(8)
	s_barrier
	s_waitcnt lgkmcnt(0)
	s_setprio 1
	s_waitcnt lgkmcnt(0)
	v_mfma_f32_16x16x32_bf16 v[124:127], v[128:131], v[168:171], 0
	v_mfma_f32_16x16x32_bf16 v[120:123], v[136:139], v[168:171], 0
	v_mfma_f32_16x16x32_bf16 v[112:115], v[128:131], v[192:195], 0
	v_mfma_f32_16x16x32_bf16 v[104:107], v[136:139], v[192:195], 0
	v_mfma_f32_16x16x32_bf16 v[96:99], v[128:131], v[200:203], 0
	v_mfma_f32_16x16x32_bf16 v[88:91], v[136:139], v[200:203], 0
	v_mfma_f32_16x16x32_bf16 v[80:83], v[128:131], v[208:211], 0
	v_mfma_f32_16x16x32_bf16 v[72:75], v[136:139], v[208:211], 0
	v_mfma_f32_16x16x32_bf16 v[124:127], v[132:135], v[188:191], v[124:127]
	v_mfma_f32_16x16x32_bf16 v[120:123], v[140:143], v[188:191], v[120:123]
	v_mfma_f32_16x16x32_bf16 v[112:115], v[132:135], v[196:199], v[112:115]
	v_mfma_f32_16x16x32_bf16 v[104:107], v[140:143], v[196:199], v[104:107]
	v_mfma_f32_16x16x32_bf16 v[96:99], v[132:135], v[204:207], v[96:99]
	v_mfma_f32_16x16x32_bf16 v[88:91], v[140:143], v[204:207], v[88:91]
	v_mfma_f32_16x16x32_bf16 v[80:83], v[132:135], v[212:215], v[80:83]
	v_mfma_f32_16x16x32_bf16 v[72:75], v[140:143], v[212:215], v[72:75]
	s_setprio 0
	s_barrier
	s_add_i32 s96, 0, 0x14000
	s_add_i32 s95, s95, s50
	v_add_u32_e32 v228, s96, v173
	v_lshl_add_u64 v[232:233], s[44:45], 0, v[148:149]
	s_mov_b32 m0, s95
	ds_read_b128 v[216:219], v228
	ds_read_b128 v[220:223], v228 offset:1024
	ds_read_b128 v[224:227], v228 offset:2048
	ds_read_b128 v[228:231], v228 offset:3072
	global_load_lds_dwordx4 v[232:233], off
	v_lshl_add_u64 v[234:235], s[44:45], 0, v[158:159]
	s_add_i32 m0, s95, 0x2000
	s_nop 0
	global_load_lds_dwordx4 v[234:235], off
	s_barrier
	s_waitcnt lgkmcnt(0)
	s_setprio 1
	s_waitcnt lgkmcnt(0)
	v_mfma_f32_16x16x32_bf16 v[116:119], v[216:219], v[168:171], 0
	v_mfma_f32_16x16x32_bf16 v[108:111], v[224:227], v[168:171], 0
	v_mfma_f32_16x16x32_bf16 v[100:103], v[216:219], v[192:195], 0
	v_mfma_f32_16x16x32_bf16 v[92:95], v[224:227], v[192:195], 0
	v_mfma_f32_16x16x32_bf16 v[84:87], v[216:219], v[200:203], 0
	v_mfma_f32_16x16x32_bf16 v[76:79], v[224:227], v[200:203], 0
	v_mfma_f32_16x16x32_bf16 v[68:71], v[216:219], v[208:211], 0
	v_mfma_f32_16x16x32_bf16 v[64:67], v[224:227], v[208:211], 0
	v_mfma_f32_16x16x32_bf16 v[116:119], v[220:223], v[188:191], v[116:119]
	v_mfma_f32_16x16x32_bf16 v[108:111], v[228:231], v[188:191], v[108:111]
	v_mfma_f32_16x16x32_bf16 v[100:103], v[220:223], v[196:199], v[100:103]
	v_mfma_f32_16x16x32_bf16 v[92:95], v[228:231], v[196:199], v[92:95]
	v_mfma_f32_16x16x32_bf16 v[84:87], v[220:223], v[204:207], v[84:87]
	v_mfma_f32_16x16x32_bf16 v[76:79], v[228:231], v[204:207], v[76:79]
	v_mfma_f32_16x16x32_bf16 v[68:71], v[220:223], v[212:215], v[68:71]
	v_mfma_f32_16x16x32_bf16 v[64:67], v[228:231], v[212:215], v[64:67]
	s_setprio 0
	s_mov_b32 m0, s51
	v_lshl_add_u64 v[236:237], s[42:43], 0, v[162:163]
	s_barrier
	ds_read_b128 v[168:171], v175 offset:16384
	ds_read_b128 v[188:191], v175 offset:17408
	ds_read_b128 v[192:195], v175 offset:18432
	ds_read_b128 v[196:199], v175 offset:19456
	ds_read_b128 v[200:203], v175 offset:20480
	ds_read_b128 v[204:207], v175 offset:21504
	ds_read_b128 v[208:211], v175 offset:22528
	ds_read_b128 v[212:215], v175 offset:23552
	global_load_lds_dwordx4 v[236:237], off
	v_lshl_add_u64 v[238:239], s[42:43], 0, v[160:161]
	s_mov_b32 m0, s74
	s_nop 0
	global_load_lds_dwordx4 v[238:239], off
	s_barrier
	s_waitcnt lgkmcnt(0)
	s_setprio 1
	s_waitcnt lgkmcnt(0)
	v_mfma_f32_16x16x32_bf16 v[60:63], v[128:131], v[168:171], 0
	v_mfma_f32_16x16x32_bf16 v[56:59], v[136:139], v[168:171], 0
	v_mfma_f32_16x16x32_bf16 v[52:55], v[128:131], v[192:195], 0
	v_mfma_f32_16x16x32_bf16 v[44:47], v[136:139], v[192:195], 0
	v_mfma_f32_16x16x32_bf16 v[36:39], v[128:131], v[200:203], 0
	v_mfma_f32_16x16x32_bf16 v[28:31], v[136:139], v[200:203], 0
	v_mfma_f32_16x16x32_bf16 v[20:23], v[128:131], v[208:211], 0
	v_mfma_f32_16x16x32_bf16 v[12:15], v[136:139], v[208:211], 0
	v_mfma_f32_16x16x32_bf16 v[60:63], v[132:135], v[188:191], v[60:63]
	v_mfma_f32_16x16x32_bf16 v[56:59], v[140:143], v[188:191], v[56:59]
	v_mfma_f32_16x16x32_bf16 v[52:55], v[132:135], v[196:199], v[52:55]
	v_mfma_f32_16x16x32_bf16 v[44:47], v[140:143], v[196:199], v[44:47]
	v_mfma_f32_16x16x32_bf16 v[36:39], v[132:135], v[204:207], v[36:39]
	v_mfma_f32_16x16x32_bf16 v[28:31], v[140:143], v[204:207], v[28:31]
	v_mfma_f32_16x16x32_bf16 v[20:23], v[132:135], v[212:215], v[20:23]
	v_mfma_f32_16x16x32_bf16 v[12:15], v[140:143], v[212:215], v[12:15]
	s_setprio 0
	s_barrier
	s_add_u32 s44, s44, s11
	s_addc_u32 s45, s45, 0
	s_add_i32 s95, s96, s50
	v_lshl_add_u64 v[240:241], s[44:45], 0, v[148:149]
	s_mov_b32 m0, s95
	v_lshl_add_u64 v[242:243], s[44:45], 0, v[158:159]
	global_load_lds_dwordx4 v[240:241], off
	s_add_i32 m0, s95, 0x2000
	s_nop 0
	global_load_lds_dwordx4 v[242:243], off
	s_waitcnt vmcnt(6)
	s_barrier
	s_setprio 1
	v_mfma_f32_16x16x32_bf16 v[48:51], v[216:219], v[168:171], 0
	v_mfma_f32_16x16x32_bf16 v[40:43], v[224:227], v[168:171], 0
	v_mfma_f32_16x16x32_bf16 v[32:35], v[216:219], v[192:195], 0
	v_mfma_f32_16x16x32_bf16 v[24:27], v[224:227], v[192:195], 0
	v_mfma_f32_16x16x32_bf16 v[16:19], v[216:219], v[200:203], 0
	v_mfma_f32_16x16x32_bf16 v[8:11], v[224:227], v[200:203], 0
	v_mfma_f32_16x16x32_bf16 v[4:7], v[216:219], v[208:211], 0
	v_mfma_f32_16x16x32_bf16 v[0:3], v[224:227], v[208:211], 0
	v_mfma_f32_16x16x32_bf16 v[48:51], v[220:223], v[188:191], v[48:51]
	v_mfma_f32_16x16x32_bf16 v[40:43], v[228:231], v[188:191], v[40:43]
	v_mfma_f32_16x16x32_bf16 v[32:35], v[220:223], v[196:199], v[32:35]
	v_mfma_f32_16x16x32_bf16 v[24:27], v[228:231], v[196:199], v[24:27]
	v_mfma_f32_16x16x32_bf16 v[16:19], v[220:223], v[204:207], v[16:19]
	v_mfma_f32_16x16x32_bf16 v[8:11], v[228:231], v[204:207], v[8:11]
	v_mfma_f32_16x16x32_bf16 v[4:7], v[220:223], v[212:215], v[4:7]
	v_mfma_f32_16x16x32_bf16 v[0:3], v[228:231], v[212:215], v[0:3]
	s_setprio 0
	s_add_i32 s44, 0, 0x18000
	v_add_u32_e32 v140, s44, v173
	s_barrier
	ds_read_b128 v[128:131], v140
	ds_read_b128 v[132:135], v140 offset:1024
	ds_read_b128 v[136:139], v140 offset:2048
	ds_read_b128 v[140:143], v140 offset:3072
	s_add_u32 s42, s42, s84
	s_addc_u32 s43, s43, 0
	s_mov_b32 m0, s75
	v_lshl_add_u64 v[216:217], s[42:43], 0, v[162:163]
	ds_read_b128 v[168:171], v175 offset:32768
	ds_read_b128 v[188:191], v175 offset:33792
	ds_read_b128 v[192:195], v175 offset:34816
	ds_read_b128 v[196:199], v175 offset:35840
	ds_read_b128 v[200:203], v175 offset:36864
	ds_read_b128 v[204:207], v175 offset:37888
	ds_read_b128 v[208:211], v175 offset:38912
	ds_read_b128 v[212:215], v175 offset:39936
	global_load_lds_dwordx4 v[216:217], off
	v_lshl_add_u64 v[216:217], s[42:43], 0, v[160:161]
	s_mov_b32 m0, s78
	s_nop 0
	global_load_lds_dwordx4 v[216:217], off
	s_waitcnt lgkmcnt(8)
	s_barrier
	s_waitcnt lgkmcnt(0)
	s_setprio 1
	s_waitcnt lgkmcnt(0)
	v_mfma_f32_16x16x32_bf16 v[124:127], v[128:131], v[168:171], v[124:127]
	v_mfma_f32_16x16x32_bf16 v[120:123], v[136:139], v[168:171], v[120:123]
	v_mfma_f32_16x16x32_bf16 v[112:115], v[128:131], v[192:195], v[112:115]
	v_mfma_f32_16x16x32_bf16 v[104:107], v[136:139], v[192:195], v[104:107]
	v_mfma_f32_16x16x32_bf16 v[96:99], v[128:131], v[200:203], v[96:99]
	v_mfma_f32_16x16x32_bf16 v[88:91], v[136:139], v[200:203], v[88:91]
	v_mfma_f32_16x16x32_bf16 v[80:83], v[128:131], v[208:211], v[80:83]
	v_mfma_f32_16x16x32_bf16 v[72:75], v[136:139], v[208:211], v[72:75]
	v_mfma_f32_16x16x32_bf16 v[124:127], v[132:135], v[188:191], v[124:127]
	v_mfma_f32_16x16x32_bf16 v[120:123], v[140:143], v[188:191], v[120:123]
	v_mfma_f32_16x16x32_bf16 v[112:115], v[132:135], v[196:199], v[112:115]
	v_mfma_f32_16x16x32_bf16 v[104:107], v[140:143], v[196:199], v[104:107]
	v_mfma_f32_16x16x32_bf16 v[96:99], v[132:135], v[204:207], v[96:99]
	v_mfma_f32_16x16x32_bf16 v[88:91], v[140:143], v[204:207], v[88:91]
	v_mfma_f32_16x16x32_bf16 v[80:83], v[132:135], v[212:215], v[80:83]
	v_mfma_f32_16x16x32_bf16 v[72:75], v[140:143], v[212:215], v[72:75]
	s_setprio 0
	s_barrier
	s_add_i32 s42, 0, 0x1c000
	s_add_i32 s43, s44, s50
	v_add_u32_e32 v228, s42, v173
	v_lshl_add_u64 v[232:233], v[232:233], 0, s[28:29]
	s_mov_b32 m0, s43
	ds_read_b128 v[216:219], v228
	ds_read_b128 v[220:223], v228 offset:1024
	ds_read_b128 v[224:227], v228 offset:2048
	ds_read_b128 v[228:231], v228 offset:3072
	global_load_lds_dwordx4 v[232:233], off
	v_lshl_add_u64 v[232:233], v[234:235], 0, s[28:29]
	s_add_i32 m0, s43, 0x2000
	s_nop 0
	global_load_lds_dwordx4 v[232:233], off
	s_barrier
	s_waitcnt lgkmcnt(0)
	s_setprio 1
	s_waitcnt lgkmcnt(0)
	v_mfma_f32_16x16x32_bf16 v[116:119], v[216:219], v[168:171], v[116:119]
	v_mfma_f32_16x16x32_bf16 v[108:111], v[224:227], v[168:171], v[108:111]
	v_mfma_f32_16x16x32_bf16 v[100:103], v[216:219], v[192:195], v[100:103]
	v_mfma_f32_16x16x32_bf16 v[92:95], v[224:227], v[192:195], v[92:95]
	v_mfma_f32_16x16x32_bf16 v[84:87], v[216:219], v[200:203], v[84:87]
	v_mfma_f32_16x16x32_bf16 v[76:79], v[224:227], v[200:203], v[76:79]
	v_mfma_f32_16x16x32_bf16 v[68:71], v[216:219], v[208:211], v[68:71]
	v_mfma_f32_16x16x32_bf16 v[64:67], v[224:227], v[208:211], v[64:67]
	v_mfma_f32_16x16x32_bf16 v[116:119], v[220:223], v[188:191], v[116:119]
	v_mfma_f32_16x16x32_bf16 v[108:111], v[228:231], v[188:191], v[108:111]
	v_mfma_f32_16x16x32_bf16 v[100:103], v[220:223], v[196:199], v[100:103]
	v_mfma_f32_16x16x32_bf16 v[92:95], v[228:231], v[196:199], v[92:95]
	v_mfma_f32_16x16x32_bf16 v[84:87], v[220:223], v[204:207], v[84:87]
	v_mfma_f32_16x16x32_bf16 v[76:79], v[228:231], v[204:207], v[76:79]
	v_mfma_f32_16x16x32_bf16 v[68:71], v[220:223], v[212:215], v[68:71]
	v_mfma_f32_16x16x32_bf16 v[64:67], v[228:231], v[212:215], v[64:67]
	s_setprio 0
	s_mov_b32 m0, s80
	v_lshl_add_u64 v[232:233], v[236:237], 0, s[28:29]
	s_barrier
	ds_read_b128 v[168:171], v175 offset:49152
	ds_read_b128 v[188:191], v175 offset:50176
	ds_read_b128 v[192:195], v175 offset:51200
	ds_read_b128 v[196:199], v175 offset:52224
	ds_read_b128 v[200:203], v175 offset:53248
	ds_read_b128 v[204:207], v175 offset:54272
	ds_read_b128 v[208:211], v175 offset:55296
	ds_read_b128 v[212:215], v175 offset:56320
	global_load_lds_dwordx4 v[232:233], off
	v_lshl_add_u64 v[232:233], v[238:239], 0, s[28:29]
	s_mov_b32 m0, s81
	s_nop 0
	global_load_lds_dwordx4 v[232:233], off
	s_barrier
	s_waitcnt lgkmcnt(0)
	s_setprio 1
	s_waitcnt lgkmcnt(0)
	v_mfma_f32_16x16x32_bf16 v[60:63], v[128:131], v[168:171], v[60:63]
	v_mfma_f32_16x16x32_bf16 v[56:59], v[136:139], v[168:171], v[56:59]
	v_mfma_f32_16x16x32_bf16 v[52:55], v[128:131], v[192:195], v[52:55]
	v_mfma_f32_16x16x32_bf16 v[44:47], v[136:139], v[192:195], v[44:47]
	v_mfma_f32_16x16x32_bf16 v[36:39], v[128:131], v[200:203], v[36:39]
	v_mfma_f32_16x16x32_bf16 v[28:31], v[136:139], v[200:203], v[28:31]
	v_mfma_f32_16x16x32_bf16 v[20:23], v[128:131], v[208:211], v[20:23]
	v_mfma_f32_16x16x32_bf16 v[12:15], v[136:139], v[208:211], v[12:15]
	v_mfma_f32_16x16x32_bf16 v[60:63], v[132:135], v[188:191], v[60:63]
	v_mfma_f32_16x16x32_bf16 v[56:59], v[140:143], v[188:191], v[56:59]
	v_mfma_f32_16x16x32_bf16 v[52:55], v[132:135], v[196:199], v[52:55]
	v_mfma_f32_16x16x32_bf16 v[44:47], v[140:143], v[196:199], v[44:47]
	v_mfma_f32_16x16x32_bf16 v[36:39], v[132:135], v[204:207], v[36:39]
	v_mfma_f32_16x16x32_bf16 v[28:31], v[140:143], v[204:207], v[28:31]
	v_mfma_f32_16x16x32_bf16 v[20:23], v[132:135], v[212:215], v[20:23]
	v_mfma_f32_16x16x32_bf16 v[12:15], v[140:143], v[212:215], v[12:15]
	s_setprio 0
	s_barrier
	s_add_i32 s42, s42, s50
	v_lshl_add_u64 v[128:129], v[240:241], 0, s[28:29]
	s_mov_b32 m0, s42
	s_nop 0
	global_load_lds_dwordx4 v[128:129], off
	v_lshl_add_u64 v[128:129], v[242:243], 0, s[28:29]
	s_add_i32 m0, s42, 0x2000
	s_nop 0
	global_load_lds_dwordx4 v[128:129], off
	s_waitcnt vmcnt(6)
	s_barrier
	s_setprio 1
	v_mfma_f32_16x16x32_bf16 v[48:51], v[216:219], v[168:171], v[48:51]
	v_mfma_f32_16x16x32_bf16 v[40:43], v[224:227], v[168:171], v[40:43]
	v_mfma_f32_16x16x32_bf16 v[32:35], v[216:219], v[192:195], v[32:35]
	v_mfma_f32_16x16x32_bf16 v[24:27], v[224:227], v[192:195], v[24:27]
	v_mfma_f32_16x16x32_bf16 v[16:19], v[216:219], v[200:203], v[16:19]
	v_mfma_f32_16x16x32_bf16 v[8:11], v[224:227], v[200:203], v[8:11]
	v_mfma_f32_16x16x32_bf16 v[4:7], v[216:219], v[208:211], v[4:7]
	v_mfma_f32_16x16x32_bf16 v[0:3], v[224:227], v[208:211], v[0:3]
	v_mfma_f32_16x16x32_bf16 v[48:51], v[220:223], v[188:191], v[48:51]
	v_mfma_f32_16x16x32_bf16 v[40:43], v[228:231], v[188:191], v[40:43]
	v_mfma_f32_16x16x32_bf16 v[32:35], v[220:223], v[196:199], v[32:35]
	v_mfma_f32_16x16x32_bf16 v[24:27], v[228:231], v[196:199], v[24:27]
	v_mfma_f32_16x16x32_bf16 v[16:19], v[220:223], v[204:207], v[16:19]
	v_mfma_f32_16x16x32_bf16 v[8:11], v[228:231], v[204:207], v[8:11]
	v_mfma_f32_16x16x32_bf16 v[4:7], v[220:223], v[212:215], v[4:7]
	v_mfma_f32_16x16x32_bf16 v[0:3], v[228:231], v[212:215], v[0:3]
	s_setprio 0
	s_add_u32 s0, s0, 0x100
	s_addc_u32 s1, s1, 0
	s_add_u32 vcc_lo, vcc_lo, 0x100
	s_addc_u32 vcc_hi, vcc_hi, 0
	s_cmp_ge_u32 s94, s88
	s_mov_b32 s42, s94
	s_barrier
	s_cbranch_scc1 .Lpeel_after_g2

.Lpeel_after_g2:
	v_lshl_or_b32 v168, s93, 8, v174
	v_ashrrev_i32_e32 v169, 31, v168
	v_cndmask_b32_e64 v129, 0, 1, s[8:9]
	v_lshl_add_u64 v[170:171], v[168:169], 2, s[24:25]
	v_mov_b32_e32 v128, 1.0
	v_cmp_ne_u32_e64 s[0:1], 1, v129
	s_andn2_b64 vcc, exec, s[8:9]
	v_mov_b32_e32 v132, 1.0
	v_mov_b32_e32 v133, 1.0
	v_mov_b32_e32 v134, 1.0
	v_mov_b32_e32 v135, 1.0
	s_cbranch_vccnz .LBB0_493
	global_load_dwordx4 v[132:135], v[170:171], off

.LBB0_704:
	s_ashr_i32 s3, s2, 31
	v_cmp_lt_i64_e32 vcc, s[4:5], v[152:153]
	s_lshl_b64 s[4:5], s[2:3], 19
	s_add_u32 s4, s68, s4
	s_addc_u32 s5, s69, s5
	s_and_b64 s[8:9], vcc, exec
	s_cselect_b32 s3, s5, s11
	s_cselect_b32 s45, s4, s10
	s_ashr_i32 s1, s0, 31
	s_lshl_b64 s[8:9], s[0:1], 19
	s_add_u32 s8, s65, s8
	s_addc_u32 s9, s72, s9
	s_and_b64 s[20:21], vcc, exec
	s_cselect_b32 s1, s9, s15
	s_cselect_b32 s46, s8, s14
	s_add_u32 s10, s10, 0x40080
	s_addc_u32 s11, s11, 0
	s_add_u32 s47, s14, 0x100
	v_mov_b32_e32 v0, 0
	s_addc_u32 s50, s15, 0
	s_mov_b32 s51, -2
	s_add_u32 s14, s10, 0xfffc0080
	s_addc_u32 s15, s11, -1
	s_add_i32 s73, 0, 0x10000
	v_add_u32_e32 v138, s73, v141
	ds_read_b128 v[158:161], v138
	ds_read_b128 v[162:165], v138 offset:1024
	ds_read_b128 v[166:169], v138 offset:2048
	ds_read_b128 v[170:173], v138 offset:3072
	s_cmp_eq_u32 s51, 12
	s_cselect_b32 s21, s3, s15
	s_cselect_b32 s20, s45, s14
	s_cselect_b32 s15, s1, s50
	s_cselect_b32 s14, s46, s47
	v_lshl_add_u64 v[138:139], s[10:11], 0, v[134:135]
	s_add_i32 m0, s24, 0xc000
	ds_read_b128 v[188:191], v143
	ds_read_b128 v[192:195], v143 offset:1024
	ds_read_b128 v[196:199], v143 offset:2048
	ds_read_b128 v[200:203], v143 offset:3072
	ds_read_b128 v[204:207], v143 offset:4096
	ds_read_b128 v[208:211], v143 offset:5120
	ds_read_b128 v[212:215], v143 offset:6144
	ds_read_b128 v[216:219], v143 offset:7168
	global_load_lds_dwordx4 v[138:139], off
	v_lshl_add_u64 v[138:139], s[10:11], 0, v[136:137]
	s_add_i32 m0, s24, 0xe000
	s_nop 0
	global_load_lds_dwordx4 v[138:139], off
	s_waitcnt lgkmcnt(8)
	s_barrier
	s_waitcnt lgkmcnt(0)
	s_setprio 1
	s_waitcnt lgkmcnt(0)
	v_mfma_f32_16x16x32_bf16 v[124:127], v[158:161], v[188:191], 0
	v_mfma_f32_16x16x32_bf16 v[120:123], v[166:169], v[188:191], 0
	v_mfma_f32_16x16x32_bf16 v[108:111], v[158:161], v[196:199], 0
	v_mfma_f32_16x16x32_bf16 v[104:107], v[166:169], v[196:199], 0
	v_mfma_f32_16x16x32_bf16 v[92:95], v[158:161], v[204:207], 0
	v_mfma_f32_16x16x32_bf16 v[88:91], v[166:169], v[204:207], 0
	v_mfma_f32_16x16x32_bf16 v[76:79], v[158:161], v[212:215], 0
	v_mfma_f32_16x16x32_bf16 v[72:75], v[166:169], v[212:215], 0
	v_mfma_f32_16x16x32_bf16 v[124:127], v[162:165], v[192:195], v[124:127]
	v_mfma_f32_16x16x32_bf16 v[120:123], v[170:173], v[192:195], v[120:123]
	v_mfma_f32_16x16x32_bf16 v[108:111], v[162:165], v[200:203], v[108:111]
	v_mfma_f32_16x16x32_bf16 v[104:107], v[170:173], v[200:203], v[104:107]
	v_mfma_f32_16x16x32_bf16 v[92:95], v[162:165], v[208:211], v[92:95]
	v_mfma_f32_16x16x32_bf16 v[88:91], v[170:173], v[208:211], v[88:91]
	v_mfma_f32_16x16x32_bf16 v[76:79], v[162:165], v[216:219], v[76:79]
	v_mfma_f32_16x16x32_bf16 v[72:75], v[170:173], v[216:219], v[72:75]
	s_setprio 0
	s_barrier
	s_add_i32 s78, 0, 0x14000
	v_add_u32_e32 v138, s78, v141
	s_add_i32 s73, s73, s23
	ds_read_b128 v[220:223], v138
	ds_read_b128 v[224:227], v138 offset:1024
	ds_read_b128 v[228:231], v138 offset:2048
	ds_read_b128 v[232:235], v138 offset:3072
	v_lshl_add_u64 v[138:139], s[14:15], 0, v[148:149]
	s_mov_b32 m0, s73
	v_lshl_add_u64 v[174:175], s[14:15], 0, v[128:129]
	global_load_lds_dwordx4 v[138:139], off
	s_add_i32 m0, s73, 0x2000
	s_nop 0
	global_load_lds_dwordx4 v[174:175], off
	s_barrier
	s_waitcnt lgkmcnt(0)
	s_setprio 1
	s_waitcnt lgkmcnt(0)
	v_mfma_f32_16x16x32_bf16 v[116:119], v[220:223], v[188:191], 0
	v_mfma_f32_16x16x32_bf16 v[112:115], v[228:231], v[188:191], 0
	v_mfma_f32_16x16x32_bf16 v[100:103], v[220:223], v[196:199], 0
	v_mfma_f32_16x16x32_bf16 v[96:99], v[228:231], v[196:199], 0
	v_mfma_f32_16x16x32_bf16 v[84:87], v[220:223], v[204:207], 0
	v_mfma_f32_16x16x32_bf16 v[80:83], v[228:231], v[204:207], 0
	v_mfma_f32_16x16x32_bf16 v[68:71], v[220:223], v[212:215], 0
	v_mfma_f32_16x16x32_bf16 v[64:67], v[228:231], v[212:215], 0
	v_mfma_f32_16x16x32_bf16 v[116:119], v[224:227], v[192:195], v[116:119]
	v_mfma_f32_16x16x32_bf16 v[112:115], v[232:235], v[192:195], v[112:115]
	v_mfma_f32_16x16x32_bf16 v[100:103], v[224:227], v[200:203], v[100:103]
	v_mfma_f32_16x16x32_bf16 v[96:99], v[232:235], v[200:203], v[96:99]
	v_mfma_f32_16x16x32_bf16 v[84:87], v[224:227], v[208:211], v[84:87]
	v_mfma_f32_16x16x32_bf16 v[80:83], v[232:235], v[208:211], v[80:83]
	v_mfma_f32_16x16x32_bf16 v[68:71], v[224:227], v[216:219], v[68:71]
	v_mfma_f32_16x16x32_bf16 v[64:67], v[232:235], v[216:219], v[64:67]
	s_setprio 0
	s_mov_b32 m0, s24
	v_lshl_add_u64 v[236:237], s[20:21], 0, v[132:133]
	s_barrier
	ds_read_b128 v[188:191], v143 offset:16384
	ds_read_b128 v[192:195], v143 offset:17408
	ds_read_b128 v[196:199], v143 offset:18432
	ds_read_b128 v[200:203], v143 offset:19456
	ds_read_b128 v[204:207], v143 offset:20480
	ds_read_b128 v[208:211], v143 offset:21504
	ds_read_b128 v[212:215], v143 offset:22528
	ds_read_b128 v[216:219], v143 offset:23552
	global_load_lds_dwordx4 v[236:237], off
	v_lshl_add_u64 v[238:239], s[20:21], 0, v[130:131]
	s_mov_b32 m0, s25
	s_nop 0
	global_load_lds_dwordx4 v[238:239], off
	s_barrier
	s_waitcnt lgkmcnt(0)
	s_setprio 1
	s_waitcnt lgkmcnt(0)
	v_mfma_f32_16x16x32_bf16 v[60:63], v[158:161], v[188:191], 0
	v_mfma_f32_16x16x32_bf16 v[56:59], v[166:169], v[188:191], 0
	v_mfma_f32_16x16x32_bf16 v[44:47], v[158:161], v[196:199], 0
	v_mfma_f32_16x16x32_bf16 v[40:43], v[166:169], v[196:199], 0
	v_mfma_f32_16x16x32_bf16 v[28:31], v[158:161], v[204:207], 0
	v_mfma_f32_16x16x32_bf16 v[24:27], v[166:169], v[204:207], 0
	v_mfma_f32_16x16x32_bf16 v[12:15], v[158:161], v[212:215], 0
	v_mfma_f32_16x16x32_bf16 v[8:11], v[166:169], v[212:215], 0
	v_mfma_f32_16x16x32_bf16 v[60:63], v[162:165], v[192:195], v[60:63]
	v_mfma_f32_16x16x32_bf16 v[56:59], v[170:173], v[192:195], v[56:59]
	v_mfma_f32_16x16x32_bf16 v[44:47], v[162:165], v[200:203], v[44:47]
	v_mfma_f32_16x16x32_bf16 v[40:43], v[170:173], v[200:203], v[40:43]
	v_mfma_f32_16x16x32_bf16 v[28:31], v[162:165], v[208:211], v[28:31]
	v_mfma_f32_16x16x32_bf16 v[24:27], v[170:173], v[208:211], v[24:27]
	v_mfma_f32_16x16x32_bf16 v[12:15], v[162:165], v[216:219], v[12:15]
	v_mfma_f32_16x16x32_bf16 v[8:11], v[170:173], v[216:219], v[8:11]
	s_setprio 0
	s_barrier
	s_add_u32 s74, s14, 0x40000
	s_addc_u32 s75, s15, 0
	s_add_i32 s73, s78, s23
	v_lshl_add_u64 v[158:159], s[74:75], 0, v[148:149]
	s_mov_b32 m0, s73
	s_nop 0
	global_load_lds_dwordx4 v[158:159], off
	v_lshl_add_u64 v[158:159], s[74:75], 0, v[128:129]
	s_add_i32 m0, s73, 0x2000
	s_nop 0
	global_load_lds_dwordx4 v[158:159], off
	s_waitcnt vmcnt(6)
	s_barrier
	s_setprio 1
	v_mfma_f32_16x16x32_bf16 v[52:55], v[220:223], v[188:191], 0
	v_mfma_f32_16x16x32_bf16 v[48:51], v[228:231], v[188:191], 0
	v_mfma_f32_16x16x32_bf16 v[36:39], v[220:223], v[196:199], 0
	v_mfma_f32_16x16x32_bf16 v[32:35], v[228:231], v[196:199], 0
	v_mfma_f32_16x16x32_bf16 v[20:23], v[220:223], v[204:207], 0
	v_mfma_f32_16x16x32_bf16 v[16:19], v[228:231], v[204:207], 0
	v_mfma_f32_16x16x32_bf16 v[4:7], v[220:223], v[212:215], 0
	v_mfma_f32_16x16x32_bf16 v[0:3], v[228:231], v[212:215], 0
	v_mfma_f32_16x16x32_bf16 v[52:55], v[224:227], v[192:195], v[52:55]
	v_mfma_f32_16x16x32_bf16 v[48:51], v[232:235], v[192:195], v[48:51]
	v_mfma_f32_16x16x32_bf16 v[36:39], v[224:227], v[200:203], v[36:39]
	v_mfma_f32_16x16x32_bf16 v[32:35], v[232:235], v[200:203], v[32:35]
	v_mfma_f32_16x16x32_bf16 v[20:23], v[224:227], v[208:211], v[20:23]
	v_mfma_f32_16x16x32_bf16 v[16:19], v[232:235], v[208:211], v[16:19]
	v_mfma_f32_16x16x32_bf16 v[4:7], v[224:227], v[216:219], v[4:7]
	v_mfma_f32_16x16x32_bf16 v[0:3], v[232:235], v[216:219], v[0:3]
	s_setprio 0
	s_add_i32 s73, 0, 0x18000
	v_add_u32_e32 v170, s73, v141
	s_barrier
	ds_read_b128 v[158:161], v170
	ds_read_b128 v[162:165], v170 offset:1024
	ds_read_b128 v[166:169], v170 offset:2048
	ds_read_b128 v[170:173], v170 offset:3072
	s_add_u32 s20, s20, 0x40000
	s_addc_u32 s21, s21, 0
	s_mov_b32 m0, s36
	v_lshl_add_u64 v[220:221], s[20:21], 0, v[132:133]
	ds_read_b128 v[188:191], v143 offset:32768
	ds_read_b128 v[192:195], v143 offset:33792
	ds_read_b128 v[196:199], v143 offset:34816
	ds_read_b128 v[200:203], v143 offset:35840
	ds_read_b128 v[204:207], v143 offset:36864
	ds_read_b128 v[208:211], v143 offset:37888
	ds_read_b128 v[212:215], v143 offset:38912
	ds_read_b128 v[216:219], v143 offset:39936
	global_load_lds_dwordx4 v[220:221], off
	v_lshl_add_u64 v[220:221], s[20:21], 0, v[130:131]
	s_mov_b32 m0, s37
	s_nop 0
	global_load_lds_dwordx4 v[220:221], off
	s_waitcnt lgkmcnt(8)
	s_barrier
	s_waitcnt lgkmcnt(0)
	s_setprio 1
	s_waitcnt lgkmcnt(0)
	v_mfma_f32_16x16x32_bf16 v[124:127], v[158:161], v[188:191], v[124:127]
	v_mfma_f32_16x16x32_bf16 v[120:123], v[166:169], v[188:191], v[120:123]
	v_mfma_f32_16x16x32_bf16 v[108:111], v[158:161], v[196:199], v[108:111]
	v_mfma_f32_16x16x32_bf16 v[104:107], v[166:169], v[196:199], v[104:107]
	v_mfma_f32_16x16x32_bf16 v[92:95], v[158:161], v[204:207], v[92:95]
	v_mfma_f32_16x16x32_bf16 v[88:91], v[166:169], v[204:207], v[88:91]
	v_mfma_f32_16x16x32_bf16 v[76:79], v[158:161], v[212:215], v[76:79]
	v_mfma_f32_16x16x32_bf16 v[72:75], v[166:169], v[212:215], v[72:75]
	v_mfma_f32_16x16x32_bf16 v[124:127], v[162:165], v[192:195], v[124:127]
	v_mfma_f32_16x16x32_bf16 v[120:123], v[170:173], v[192:195], v[120:123]
	v_mfma_f32_16x16x32_bf16 v[108:111], v[162:165], v[200:203], v[108:111]
	v_mfma_f32_16x16x32_bf16 v[104:107], v[170:173], v[200:203], v[104:107]
	v_mfma_f32_16x16x32_bf16 v[92:95], v[162:165], v[208:211], v[92:95]
	v_mfma_f32_16x16x32_bf16 v[88:91], v[170:173], v[208:211], v[88:91]
	v_mfma_f32_16x16x32_bf16 v[76:79], v[162:165], v[216:219], v[76:79]
	v_mfma_f32_16x16x32_bf16 v[72:75], v[170:173], v[216:219], v[72:75]
	s_setprio 0
	s_barrier
	s_add_i32 s20, 0, 0x1c000
	s_add_i32 s21, s73, s23
	v_add_u32_e32 v232, s20, v141
	v_lshl_add_u64 v[138:139], v[138:139], 0, s[28:29]
	s_mov_b32 m0, s21
	ds_read_b128 v[220:223], v232
	ds_read_b128 v[224:227], v232 offset:1024
	ds_read_b128 v[228:231], v232 offset:2048
	ds_read_b128 v[232:235], v232 offset:3072
	global_load_lds_dwordx4 v[138:139], off
	v_lshl_add_u64 v[138:139], v[174:175], 0, s[28:29]
	s_add_i32 m0, s21, 0x2000
	s_nop 0
	global_load_lds_dwordx4 v[138:139], off
	s_barrier
	s_waitcnt lgkmcnt(0)
	s_setprio 1
	s_waitcnt lgkmcnt(0)
	v_mfma_f32_16x16x32_bf16 v[116:119], v[220:223], v[188:191], v[116:119]
	v_mfma_f32_16x16x32_bf16 v[112:115], v[228:231], v[188:191], v[112:115]
	v_mfma_f32_16x16x32_bf16 v[100:103], v[220:223], v[196:199], v[100:103]
	v_mfma_f32_16x16x32_bf16 v[96:99], v[228:231], v[196:199], v[96:99]
	v_mfma_f32_16x16x32_bf16 v[84:87], v[220:223], v[204:207], v[84:87]
	v_mfma_f32_16x16x32_bf16 v[80:83], v[228:231], v[204:207], v[80:83]
	v_mfma_f32_16x16x32_bf16 v[68:71], v[220:223], v[212:215], v[68:71]
	v_mfma_f32_16x16x32_bf16 v[64:67], v[228:231], v[212:215], v[64:67]
	v_mfma_f32_16x16x32_bf16 v[116:119], v[224:227], v[192:195], v[116:119]
	v_mfma_f32_16x16x32_bf16 v[112:115], v[232:235], v[192:195], v[112:115]
	v_mfma_f32_16x16x32_bf16 v[100:103], v[224:227], v[200:203], v[100:103]
	v_mfma_f32_16x16x32_bf16 v[96:99], v[232:235], v[200:203], v[96:99]
	v_mfma_f32_16x16x32_bf16 v[84:87], v[224:227], v[208:211], v[84:87]
	v_mfma_f32_16x16x32_bf16 v[80:83], v[232:235], v[208:211], v[80:83]
	v_mfma_f32_16x16x32_bf16 v[68:71], v[224:227], v[216:219], v[68:71]
	v_mfma_f32_16x16x32_bf16 v[64:67], v[232:235], v[216:219], v[64:67]
	s_setprio 0
	s_mov_b32 m0, s38
	v_lshl_add_u64 v[138:139], v[236:237], 0, s[28:29]
	s_barrier
	ds_read_b128 v[188:191], v143 offset:49152
	ds_read_b128 v[192:195], v143 offset:50176
	ds_read_b128 v[196:199], v143 offset:51200
	ds_read_b128 v[200:203], v143 offset:52224
	ds_read_b128 v[204:207], v143 offset:53248
	ds_read_b128 v[208:211], v143 offset:54272
	ds_read_b128 v[212:215], v143 offset:55296
	ds_read_b128 v[216:219], v143 offset:56320
	global_load_lds_dwordx4 v[138:139], off
	v_lshl_add_u64 v[138:139], v[238:239], 0, s[28:29]
	s_mov_b32 m0, s39
	s_nop 0
	global_load_lds_dwordx4 v[138:139], off
	s_barrier
	s_waitcnt lgkmcnt(0)
	s_setprio 1
	s_waitcnt lgkmcnt(0)
	v_mfma_f32_16x16x32_bf16 v[60:63], v[158:161], v[188:191], v[60:63]
	v_mfma_f32_16x16x32_bf16 v[56:59], v[166:169], v[188:191], v[56:59]
	v_mfma_f32_16x16x32_bf16 v[44:47], v[158:161], v[196:199], v[44:47]
	v_mfma_f32_16x16x32_bf16 v[40:43], v[166:169], v[196:199], v[40:43]
	v_mfma_f32_16x16x32_bf16 v[28:31], v[158:161], v[204:207], v[28:31]
	v_mfma_f32_16x16x32_bf16 v[24:27], v[166:169], v[204:207], v[24:27]
	v_mfma_f32_16x16x32_bf16 v[12:15], v[158:161], v[212:215], v[12:15]
	v_mfma_f32_16x16x32_bf16 v[8:11], v[166:169], v[212:215], v[8:11]
	v_mfma_f32_16x16x32_bf16 v[60:63], v[162:165], v[192:195], v[60:63]
	v_mfma_f32_16x16x32_bf16 v[56:59], v[170:173], v[192:195], v[56:59]
	v_mfma_f32_16x16x32_bf16 v[44:47], v[162:165], v[200:203], v[44:47]
	v_mfma_f32_16x16x32_bf16 v[40:43], v[170:173], v[200:203], v[40:43]
	v_mfma_f32_16x16x32_bf16 v[28:31], v[162:165], v[208:211], v[28:31]
	v_mfma_f32_16x16x32_bf16 v[24:27], v[170:173], v[208:211], v[24:27]
	v_mfma_f32_16x16x32_bf16 v[12:15], v[162:165], v[216:219], v[12:15]
	v_mfma_f32_16x16x32_bf16 v[8:11], v[170:173], v[216:219], v[8:11]
	s_setprio 0
	s_barrier
	s_add_u32 s14, s14, 0x40080
	s_addc_u32 s15, s15, 0
	s_add_i32 s20, s20, s23
	v_lshl_add_u64 v[138:139], s[14:15], 0, v[148:149]
	s_mov_b32 m0, s20
	s_nop 0
	global_load_lds_dwordx4 v[138:139], off
	v_lshl_add_u64 v[138:139], s[14:15], 0, v[128:129]
	s_add_i32 m0, s20, 0x2000
	s_nop 0
	global_load_lds_dwordx4 v[138:139], off
	s_waitcnt vmcnt(6)
	s_barrier
	s_setprio 1
	v_mfma_f32_16x16x32_bf16 v[52:55], v[220:223], v[188:191], v[52:55]
	v_mfma_f32_16x16x32_bf16 v[48:51], v[228:231], v[188:191], v[48:51]
	v_mfma_f32_16x16x32_bf16 v[36:39], v[220:223], v[196:199], v[36:39]
	v_mfma_f32_16x16x32_bf16 v[32:35], v[228:231], v[196:199], v[32:35]
	v_mfma_f32_16x16x32_bf16 v[20:23], v[220:223], v[204:207], v[20:23]
	v_mfma_f32_16x16x32_bf16 v[16:19], v[228:231], v[204:207], v[16:19]
	v_mfma_f32_16x16x32_bf16 v[4:7], v[220:223], v[212:215], v[4:7]
	v_mfma_f32_16x16x32_bf16 v[0:3], v[228:231], v[212:215], v[0:3]
	v_mfma_f32_16x16x32_bf16 v[52:55], v[224:227], v[192:195], v[52:55]
	v_mfma_f32_16x16x32_bf16 v[48:51], v[232:235], v[192:195], v[48:51]
	v_mfma_f32_16x16x32_bf16 v[36:39], v[224:227], v[200:203], v[36:39]
	v_mfma_f32_16x16x32_bf16 v[32:35], v[232:235], v[200:203], v[32:35]
	v_mfma_f32_16x16x32_bf16 v[20:23], v[224:227], v[208:211], v[20:23]
	v_mfma_f32_16x16x32_bf16 v[16:19], v[232:235], v[208:211], v[16:19]
	v_mfma_f32_16x16x32_bf16 v[4:7], v[224:227], v[216:219], v[4:7]
	v_mfma_f32_16x16x32_bf16 v[0:3], v[232:235], v[216:219], v[0:3]
	s_setprio 0
	s_add_i32 s51, s51, 2
	s_add_u32 s10, s10, 0x100
	s_addc_u32 s11, s11, 0
	s_add_u32 s47, s47, 0x100
	s_addc_u32 s50, s50, 0
	s_cmp_gt_u32 s51, 13
	s_barrier
	s_cbranch_scc1 .Lpeel_after_g1

.Lpeel_after_g1:
	v_lshl_add_u32 v158, s44, 8, v140
	v_lshl_or_b32 v138, s43, 8, v142
	v_ashrrev_i32_e32 v159, 31, v158
	v_max_f32 v120, 0, v120
	v_ashrrev_i32_e32 v139, 31, v138
	v_lshlrev_b64 v[160:161], 13, v[158:159]
	v_mul_f32_e32 v159, v120, v120
	v_max_f32 v120, 0, v125
	v_max_f32 v121, 0, v121
	v_max_f32 v122, 0, v122
	v_lshl_add_u64 v[160:161], s[70:71], 0, v[160:161]
	v_lshlrev_b64 v[162:163], 1, v[138:139]
	v_max_f32 v124, 0, v124
	v_mul_f32_e32 v120, v120, v120
	v_mul_f32_e32 v125, v121, v121
	v_max_f32 v121, 0, v126
	v_mul_f32_e32 v126, v122, v122
	v_max_f32 v122, 0, v127
	v_max_f32 v123, 0, v123
	v_lshl_add_u64 v[138:139], v[160:161], 0, v[162:163]
	v_mul_f32_e32 v124, v124, v124
	v_mul_f32_e32 v121, v121, v121
	v_mul_f32_e32 v122, v122, v122
	v_mul_f32_e32 v123, v123, v123
	v_cvt_pk_bf16_f32 v120, v124, v120
	v_max_f32 v112, 0, v112
	v_cvt_pk_bf16_f32 v121, v121, v122
	v_cvt_pk_bf16_f32 v122, v159, v125
	v_cvt_pk_bf16_f32 v123, v126, v123
	global_store_dwordx4 v[138:139], v[120:123], off nt
	v_max_f32 v113, 0, v113
	v_max_f32 v114, 0, v114
	v_max_f32 v116, 0, v116
	v_max_f32 v115, 0, v115
	v_max_f32 v104, 0, v104
	s_nop 1
	v_mul_f32_e32 v120, v112, v112
	v_max_f32 v112, 0, v117
	v_mul_f32_e32 v117, v113, v113
	v_mul_f32_e32 v112, v112, v112
	v_max_f32 v113, 0, v118
	v_mul_f32_e32 v118, v114, v114
	v_max_f32 v114, 0, v119
	v_mul_f32_e32 v116, v116, v116
	v_mul_f32_e32 v113, v113, v113
	v_mul_f32_e32 v114, v114, v114
	v_mul_f32_e32 v115, v115, v115
	v_cvt_pk_bf16_f32 v112, v116, v112
	v_cvt_pk_bf16_f32 v113, v113, v114
	v_cvt_pk_bf16_f32 v114, v120, v117
	v_cvt_pk_bf16_f32 v115, v118, v115
	global_store_dwordx4 v[138:139], v[112:115], off offset:256 nt
	v_max_f32 v105, 0, v105
	v_max_f32 v106, 0, v106
	v_max_f32 v108, 0, v108
	v_max_f32 v107, 0, v107
	v_max_f32 v96, 0, v96
	s_nop 1
	v_or_b32_e32 v112, 16, v158
	v_ashrrev_i32_e32 v113, 31, v112
	v_lshlrev_b64 v[112:113], 13, v[112:113]
	v_mul_f32_e32 v114, v104, v104
	v_max_f32 v104, 0, v109
	v_lshl_add_u64 v[112:113], s[70:71], 0, v[112:113]
	v_mul_f32_e32 v104, v104, v104
	v_mul_f32_e32 v109, v105, v105
	v_max_f32 v105, 0, v110
	v_mul_f32_e32 v110, v106, v106
	v_max_f32 v106, 0, v111
	v_lshl_add_u64 v[112:113], v[112:113], 0, v[162:163]
	v_mul_f32_e32 v108, v108, v108
	v_mul_f32_e32 v105, v105, v105
	v_mul_f32_e32 v106, v106, v106
	v_mul_f32_e32 v107, v107, v107
	v_cvt_pk_bf16_f32 v104, v108, v104
	v_cvt_pk_bf16_f32 v105, v105, v106
	v_cvt_pk_bf16_f32 v106, v114, v109
	v_cvt_pk_bf16_f32 v107, v110, v107
	global_store_dwordx4 v[112:113], v[104:107], off nt
	v_max_f32 v97, 0, v97
	v_max_f32 v98, 0, v98
	v_max_f32 v100, 0, v100
	v_max_f32 v99, 0, v99
	v_max_f32 v88, 0, v88
	s_nop 1
	v_mul_f32_e32 v104, v96, v96
	v_max_f32 v96, 0, v101
	v_mul_f32_e32 v101, v97, v97
	v_mul_f32_e32 v96, v96, v96
	v_max_f32 v97, 0, v102
	v_mul_f32_e32 v102, v98, v98
	v_max_f32 v98, 0, v103
	v_mul_f32_e32 v100, v100, v100
	v_mul_f32_e32 v97, v97, v97
	v_mul_f32_e32 v98, v98, v98
	v_mul_f32_e32 v99, v99, v99
	v_cvt_pk_bf16_f32 v96, v100, v96
	v_cvt_pk_bf16_f32 v97, v97, v98
	v_cvt_pk_bf16_f32 v98, v104, v101
	v_cvt_pk_bf16_f32 v99, v102, v99
	global_store_dwordx4 v[112:113], v[96:99], off offset:256 nt
	v_max_f32 v89, 0, v89
	v_max_f32 v90, 0, v90
	v_max_f32 v92, 0, v92
	v_max_f32 v91, 0, v91
	v_max_f32 v80, 0, v80
	s_nop 1
	v_or_b32_e32 v96, 32, v158
	v_ashrrev_i32_e32 v97, 31, v96
	v_lshlrev_b64 v[96:97], 13, v[96:97]
	v_mul_f32_e32 v98, v88, v88
	v_max_f32 v88, 0, v93
	v_lshl_add_u64 v[96:97], s[70:71], 0, v[96:97]
	v_mul_f32_e32 v88, v88, v88
	v_mul_f32_e32 v93, v89, v89
	v_max_f32 v89, 0, v94
	v_mul_f32_e32 v94, v90, v90
	v_max_f32 v90, 0, v95
	v_lshl_add_u64 v[96:97], v[96:97], 0, v[162:163]
	v_mul_f32_e32 v92, v92, v92
	v_mul_f32_e32 v89, v89, v89
	v_mul_f32_e32 v90, v90, v90
	v_mul_f32_e32 v91, v91, v91
	v_cvt_pk_bf16_f32 v88, v92, v88
	v_cvt_pk_bf16_f32 v89, v89, v90
	v_cvt_pk_bf16_f32 v90, v98, v93
	v_cvt_pk_bf16_f32 v91, v94, v91
	global_store_dwordx4 v[96:97], v[88:91], off nt
	v_max_f32 v81, 0, v81
	v_max_f32 v82, 0, v82
	v_max_f32 v84, 0, v84
	v_max_f32 v83, 0, v83
	v_max_f32 v72, 0, v72
	s_nop 1
	v_mul_f32_e32 v88, v80, v80
	v_max_f32 v80, 0, v85
	v_mul_f32_e32 v85, v81, v81
	v_mul_f32_e32 v80, v80, v80
	v_max_f32 v81, 0, v86
	v_mul_f32_e32 v86, v82, v82
	v_max_f32 v82, 0, v87
	v_mul_f32_e32 v84, v84, v84
	v_mul_f32_e32 v81, v81, v81
	v_mul_f32_e32 v82, v82, v82
	v_mul_f32_e32 v83, v83, v83
	v_cvt_pk_bf16_f32 v80, v84, v80
	v_cvt_pk_bf16_f32 v81, v81, v82
	v_cvt_pk_bf16_f32 v82, v88, v85
	v_cvt_pk_bf16_f32 v83, v86, v83
	global_store_dwordx4 v[96:97], v[80:83], off offset:256 nt
	v_max_f32 v73, 0, v73
	v_max_f32 v74, 0, v74
	v_max_f32 v76, 0, v76
	v_max_f32 v75, 0, v75
	v_max_f32 v64, 0, v64
	s_nop 1
	v_or_b32_e32 v80, 48, v158
	v_ashrrev_i32_e32 v81, 31, v80
	v_lshlrev_b64 v[80:81], 13, v[80:81]
	v_mul_f32_e32 v82, v72, v72
	v_max_f32 v72, 0, v77
	v_lshl_add_u64 v[80:81], s[70:71], 0, v[80:81]
	v_mul_f32_e32 v72, v72, v72
	v_mul_f32_e32 v77, v73, v73
	v_max_f32 v73, 0, v78
	v_mul_f32_e32 v78, v74, v74
	v_max_f32 v74, 0, v79
	v_lshl_add_u64 v[80:81], v[80:81], 0, v[162:163]
	v_mul_f32_e32 v76, v76, v76
	v_mul_f32_e32 v73, v73, v73
	v_mul_f32_e32 v74, v74, v74
	v_mul_f32_e32 v75, v75, v75
	v_cvt_pk_bf16_f32 v72, v76, v72
	v_max_f32 v65, 0, v65
	v_max_f32 v66, 0, v66
	v_cvt_pk_bf16_f32 v73, v73, v74
	v_cvt_pk_bf16_f32 v74, v82, v77
	v_cvt_pk_bf16_f32 v75, v78, v75
	global_store_dwordx4 v[80:81], v[72:75], off nt
	v_max_f32 v67, 0, v67
	v_max_f32 v68, 0, v68
	v_max_f32 v56, 0, v56
	v_max_f32 v60, 0, v60
	v_max_f32 v57, 0, v57
	s_nop 1
	v_mul_f32_e32 v72, v64, v64
	v_max_f32 v64, 0, v69
	v_mul_f32_e32 v69, v65, v65
	v_max_f32 v65, 0, v70
	v_mul_f32_e32 v70, v66, v66
	v_max_f32 v66, 0, v71
	v_mul_f32_e32 v65, v65, v65
	v_mul_f32_e32 v66, v66, v66
	v_mul_f32_e32 v64, v64, v64
	v_mul_f32_e32 v67, v67, v67
	v_cvt_pk_bf16_f32 v65, v65, v66
	v_cvt_pk_bf16_f32 v66, v72, v69
	v_mul_f32_e32 v68, v68, v68
	v_cvt_pk_bf16_f32 v64, v68, v64
	v_cvt_pk_bf16_f32 v67, v70, v67
	global_store_dwordx4 v[80:81], v[64:67], off offset:256 nt
	v_max_f32 v58, 0, v58
	v_mul_f32_e32 v60, v60, v60
	s_mov_b32 s1, 0x100000
	v_mul_f32_e32 v66, v56, v56
	v_max_f32 v56, 0, v61
	v_mul_f32_e32 v61, v57, v57
	v_mul_f32_e32 v56, v56, v56
	v_max_f32 v57, 0, v62
	v_mul_f32_e32 v62, v58, v58
	v_max_f32 v58, 0, v63
	v_mul_f32_e32 v57, v57, v57
	v_max_f32 v59, 0, v59
	v_mul_f32_e32 v58, v58, v58
	v_cvt_pk_bf16_f32 v56, v60, v56
	v_add_co_u32_e32 v60, vcc, s1, v138
	v_mul_f32_e32 v59, v59, v59
	v_cvt_pk_bf16_f32 v57, v57, v58
	v_cvt_pk_bf16_f32 v58, v66, v61
	s_nop 0
	v_addc_co_u32_e32 v61, vcc, 0, v139, vcc
	v_max_f32 v48, 0, v48
	v_max_f32 v49, 0, v49
	v_max_f32 v50, 0, v50
	v_cvt_pk_bf16_f32 v59, v62, v59
	global_store_dwordx4 v[60:61], v[56:59], off nt
	s_mov_b64 s[10:11], 0x100000
	v_max_f32 v51, 0, v51
	v_lshl_add_u64 v[64:65], v[138:139], 0, s[10:11]
	v_mul_f32_e32 v56, v48, v48
	v_max_f32 v48, 0, v53
	v_mul_f32_e32 v53, v49, v49
	v_max_f32 v49, 0, v54
	v_mul_f32_e32 v54, v50, v50
	v_max_f32 v50, 0, v55
	v_mul_f32_e32 v49, v49, v49
	v_mul_f32_e32 v50, v50, v50
	v_max_f32 v52, 0, v52
	v_mul_f32_e32 v48, v48, v48
	v_mul_f32_e32 v51, v51, v51
	v_cvt_pk_bf16_f32 v49, v49, v50
	v_cvt_pk_bf16_f32 v50, v56, v53
	v_max_f32 v40, 0, v40
	v_mul_f32_e32 v52, v52, v52
	v_cvt_pk_bf16_f32 v48, v52, v48
	v_cvt_pk_bf16_f32 v51, v54, v51
	global_store_dwordx4 v[64:65], v[48:51], off offset:256 nt
	v_max_f32 v44, 0, v44
	v_max_f32 v41, 0, v41
	v_max_f32 v42, 0, v42
	s_mov_b32 s1, 0x120000
	v_mul_f32_e32 v44, v44, v44
	v_mul_f32_e32 v50, v40, v40
	v_max_f32 v40, 0, v45
	v_mul_f32_e32 v45, v41, v41
	v_mul_f32_e32 v40, v40, v40
	v_max_f32 v41, 0, v46
	v_mul_f32_e32 v46, v42, v42
	v_max_f32 v42, 0, v47
	v_mul_f32_e32 v41, v41, v41
	v_max_f32 v43, 0, v43
	v_mul_f32_e32 v42, v42, v42
	v_cvt_pk_bf16_f32 v40, v44, v40
	v_add_co_u32_e32 v44, vcc, s1, v138
	v_mul_f32_e32 v43, v43, v43
	v_cvt_pk_bf16_f32 v41, v41, v42
	v_cvt_pk_bf16_f32 v42, v50, v45
	s_nop 0
	v_addc_co_u32_e32 v45, vcc, 0, v139, vcc
	v_max_f32 v32, 0, v32
	v_max_f32 v33, 0, v33
	v_max_f32 v34, 0, v34
	v_cvt_pk_bf16_f32 v43, v46, v43
	global_store_dwordx4 v[44:45], v[40:43], off nt
	s_mov_b64 s[10:11], 0x120000
	v_max_f32 v35, 0, v35
	v_lshl_add_u64 v[48:49], v[138:139], 0, s[10:11]
	v_mul_f32_e32 v40, v32, v32
	v_max_f32 v32, 0, v37
	v_mul_f32_e32 v37, v33, v33
	v_max_f32 v33, 0, v38
	v_mul_f32_e32 v38, v34, v34
	v_max_f32 v34, 0, v39
	v_mul_f32_e32 v33, v33, v33
	v_mul_f32_e32 v34, v34, v34
	v_max_f32 v36, 0, v36
	v_mul_f32_e32 v32, v32, v32
	v_mul_f32_e32 v35, v35, v35
	v_cvt_pk_bf16_f32 v33, v33, v34
	v_cvt_pk_bf16_f32 v34, v40, v37
	v_max_f32 v24, 0, v24
	v_mul_f32_e32 v36, v36, v36
	v_cvt_pk_bf16_f32 v32, v36, v32
	v_cvt_pk_bf16_f32 v35, v38, v35
	global_store_dwordx4 v[48:49], v[32:35], off offset:256 nt
	v_max_f32 v28, 0, v28
	v_max_f32 v25, 0, v25
	v_max_f32 v26, 0, v26
	s_mov_b32 s1, 0x140000
	v_mul_f32_e32 v28, v28, v28
	v_mul_f32_e32 v34, v24, v24
	v_max_f32 v24, 0, v29
	v_mul_f32_e32 v29, v25, v25
	v_mul_f32_e32 v24, v24, v24
	v_max_f32 v25, 0, v30
	v_mul_f32_e32 v30, v26, v26
	v_max_f32 v26, 0, v31
	v_mul_f32_e32 v25, v25, v25
	v_max_f32 v27, 0, v27
	v_mul_f32_e32 v26, v26, v26
	v_cvt_pk_bf16_f32 v24, v28, v24
	v_add_co_u32_e32 v28, vcc, s1, v138
	v_mul_f32_e32 v27, v27, v27
	v_cvt_pk_bf16_f32 v25, v25, v26
	v_cvt_pk_bf16_f32 v26, v34, v29
	s_nop 0
	v_addc_co_u32_e32 v29, vcc, 0, v139, vcc
	v_max_f32 v16, 0, v16
	v_max_f32 v17, 0, v17
	v_max_f32 v18, 0, v18
	v_cvt_pk_bf16_f32 v27, v30, v27
	global_store_dwordx4 v[28:29], v[24:27], off nt
	s_mov_b64 s[10:11], 0x140000
	v_max_f32 v19, 0, v19
	v_lshl_add_u64 v[32:33], v[138:139], 0, s[10:11]
	v_mul_f32_e32 v24, v16, v16
	v_max_f32 v16, 0, v21
	v_mul_f32_e32 v21, v17, v17
	v_max_f32 v17, 0, v22
	v_mul_f32_e32 v22, v18, v18
	v_max_f32 v18, 0, v23
	v_mul_f32_e32 v17, v17, v17
	v_mul_f32_e32 v18, v18, v18
	v_max_f32 v20, 0, v20
	v_mul_f32_e32 v16, v16, v16
	v_mul_f32_e32 v19, v19, v19
	v_cvt_pk_bf16_f32 v17, v17, v18
	v_cvt_pk_bf16_f32 v18, v24, v21
	v_max_f32 v8, 0, v8
	v_mul_f32_e32 v20, v20, v20
	v_cvt_pk_bf16_f32 v16, v20, v16
	v_cvt_pk_bf16_f32 v19, v22, v19
	global_store_dwordx4 v[32:33], v[16:19], off offset:256 nt
	v_max_f32 v12, 0, v12
	v_max_f32 v9, 0, v9
	v_max_f32 v10, 0, v10
	s_mov_b32 s1, 0x160000
	v_mul_f32_e32 v12, v12, v12
	v_mul_f32_e32 v18, v8, v8
	v_max_f32 v8, 0, v13
	v_mul_f32_e32 v13, v9, v9
	v_mul_f32_e32 v8, v8, v8
	v_max_f32 v9, 0, v14
	v_mul_f32_e32 v14, v10, v10
	v_max_f32 v10, 0, v15
	v_mul_f32_e32 v9, v9, v9
	v_max_f32 v11, 0, v11
	v_mul_f32_e32 v10, v10, v10
	v_cvt_pk_bf16_f32 v8, v12, v8
	v_add_co_u32_e32 v12, vcc, s1, v138
	v_mul_f32_e32 v11, v11, v11
	v_cvt_pk_bf16_f32 v9, v9, v10
	v_cvt_pk_bf16_f32 v10, v18, v13
	s_nop 0
	v_addc_co_u32_e32 v13, vcc, 0, v139, vcc
	v_max_f32 v0, 0, v0
	v_max_f32 v1, 0, v1
	v_max_f32 v2, 0, v2
	s_mov_b64 s[10:11], 0x160000
	v_cvt_pk_bf16_f32 v11, v14, v11
	global_store_dwordx4 v[12:13], v[8:11], off nt
	v_max_f32 v3, 0, v3
	v_lshl_add_u64 v[16:17], v[138:139], 0, s[10:11]
	v_max_f32 v4, 0, v4
	v_mul_f32_e32 v3, v3, v3
	v_mul_f32_e32 v8, v0, v0
	v_max_f32 v0, 0, v5
	v_mul_f32_e32 v5, v1, v1
	v_max_f32 v1, 0, v6
	v_mul_f32_e32 v6, v2, v2
	v_max_f32 v2, 0, v7
	v_mul_f32_e32 v0, v0, v0
	v_mul_f32_e32 v1, v1, v1
	v_mul_f32_e32 v2, v2, v2
	s_and_b64 vcc, exec, s[40:41]
	s_mov_b32 s43, s0
	s_mov_b32 s44, s2
	s_mov_b64 s[14:15], s[8:9]
	s_mov_b64 s[10:11], s[4:5]
	v_mul_f32_e32 v4, v4, v4
	v_cvt_pk_bf16_f32 v0, v4, v0
	v_cvt_pk_bf16_f32 v1, v1, v2
	v_cvt_pk_bf16_f32 v2, v8, v5
	v_cvt_pk_bf16_f32 v3, v6, v3
	global_store_dwordx4 v[16:17], v[0:3], off offset:256 nt
	s_cbranch_vccz .LBB0_698
	s_waitcnt vmcnt(0)
	s_cmpk_gt_u32 s22, 0xff
	s_cbranch_scc1 .LBB0_709
	s_barrier
